# grid barrier: non-leader workgroups poll the cross-XCD generation word directly (one agent-scope hop less per barrier)
# speedup vs baseline: 1.0394x; 1.0019x over previous
.LBB0_1911:
	s_or_b64 exec, exec, s[20:21]
	v_cvt_f32_u32_e32 v5, v3
	s_waitcnt vmcnt(0)
	v_readfirstlane_b32 s20, v4
	v_sub_u32_e32 v4, 0, v3
	v_rcp_iflag_f32_e32 v5, v5
	v_add_u32_e32 v6, s20, v0
	v_mul_f32_e32 v5, 0x4f7ffffe, v5
	v_cvt_u32_f32_e32 v5, v5
	v_mul_lo_u32 v0, v4, v5
	v_mul_hi_u32 v0, v5, v0
	v_add_u32_e32 v0, v5, v0
	v_mul_hi_u32 v0, v6, v0
	v_mul_lo_u32 v4, v0, v3
	v_sub_u32_e32 v4, v6, v4
	v_add_u32_e32 v5, 1, v0
	v_cmp_ge_u32_e32 vcc, v4, v3
	s_nop 1
	v_cndmask_b32_e32 v0, v0, v5, vcc
	v_sub_u32_e32 v5, v4, v3
	v_cndmask_b32_e32 v4, v4, v5, vcc
	v_add_u32_e32 v5, 1, v0
	v_cmp_ge_u32_e32 vcc, v4, v3
	v_add_u32_e32 v4, 1, v6
	s_nop 0
	v_cndmask_b32_e32 v0, v0, v5, vcc
	v_mul_lo_u32 v5, v3, v0
	v_add_u32_e32 v3, v5, v3
	v_cmp_ne_u32_e32 vcc, v4, v3
	s_and_saveexec_b64 s[20:21], vcc
	s_xor_b64 s[20:21], exec, s[20:21]
	s_cbranch_execz .LBB0_1925
	v_readlane_b32 s24, v250, 10
	v_readlane_b32 s25, v250, 11
	s_waitcnt lgkmcnt(0)
	s_nop 3
	global_load_dword v2, v1, s[24:25] sc1
	s_waitcnt vmcnt(0)
	v_cmp_eq_u32_e32 vcc, v2, v0
	s_and_saveexec_b64 s[24:25], vcc
	s_cbranch_execz .LBB0_1924
	s_mov_b32 s23, 1
	s_mov_b64 s[36:37], 0
	s_branch .LBB0_1915
